# xcc_mode_setup: 16 census loads issued together and reduced with scalar ops instead of 14 serialized round trips
# speedup vs baseline: 1.0347x; 1.0030x over previous
.LBB0_95:
	s_or_b64 exec, exec, s[4:5]
	s_waitcnt lgkmcnt(0)
	s_barrier
	s_and_saveexec_b64 s[12:13], s[10:11]
	s_cbranch_execz .LBB0_124
	s_load_dwordx2 s[18:19], s[0:1], 0x80
	v_mov_b32_e32 v1, 0x4000
	v_mov_b32_e32 v18, 0x5000
	s_add_i32 s4, 0, 0x20174
	v_mov_b32_e32 v19, s4
	ds_read_b32 v19, v19
	s_getreg_b32 s4, hwreg(HW_REG_XCC_ID, 0, 4)
	s_and_b32 s21, s4, 15
	s_waitcnt lgkmcnt(0)
	global_load_dword v2, v1, s[18:19] offset:1024 sc1
	global_load_dword v3, v1, s[18:19] offset:1280 sc1
	global_load_dword v4, v1, s[18:19] offset:1536 sc1
	global_load_dword v5, v1, s[18:19] offset:1792 sc1
	global_load_dword v6, v1, s[18:19] offset:2048 sc1
	global_load_dword v7, v1, s[18:19] offset:2304 sc1
	global_load_dword v8, v1, s[18:19] offset:2560 sc1
	global_load_dword v9, v1, s[18:19] offset:2816 sc1
	global_load_dword v10, v1, s[18:19] offset:3072 sc1
	global_load_dword v11, v1, s[18:19] offset:3328 sc1
	global_load_dword v12, v1, s[18:19] offset:3584 sc1
	global_load_dword v13, v1, s[18:19] offset:3840 sc1
	global_load_dword v14, v18, s[18:19] sc1
	global_load_dword v15, v18, s[18:19] offset:256 sc1
	global_load_dword v16, v18, s[18:19] offset:512 sc1
	global_load_dword v17, v18, s[18:19] offset:768 sc1
	s_mov_b32 s20, 0
	s_mov_b32 s22, 0
	s_mov_b32 s23, 1
	s_waitcnt vmcnt(0)
	v_readfirstlane_b32 s4, v2
	s_cmp_lg_u32 s4, 0
	s_cselect_b32 s5, 1, 0
	s_add_i32 s22, s22, s5
	s_cmp_eq_u32 s4, 32
	s_cselect_b32 s6, 1, 0
	s_xor_b32 s7, s5, 1
	s_or_b32 s6, s6, s7
	s_and_b32 s23, s23, s6
	s_cmp_gt_u32 s21, 0
	s_cselect_b32 s7, 1, 0
	s_and_b32 s7, s7, s5
	s_add_i32 s20, s20, s7
	v_readfirstlane_b32 s4, v3
	s_cmp_lg_u32 s4, 0
	s_cselect_b32 s5, 1, 0
	s_add_i32 s22, s22, s5
	s_cmp_eq_u32 s4, 32
	s_cselect_b32 s6, 1, 0
	s_xor_b32 s7, s5, 1
	s_or_b32 s6, s6, s7
	s_and_b32 s23, s23, s6
	s_cmp_gt_u32 s21, 1
	s_cselect_b32 s7, 1, 0
	s_and_b32 s7, s7, s5
	s_add_i32 s20, s20, s7
	v_readfirstlane_b32 s4, v4
	s_cmp_lg_u32 s4, 0
	s_cselect_b32 s5, 1, 0
	s_add_i32 s22, s22, s5
	s_cmp_eq_u32 s4, 32
	s_cselect_b32 s6, 1, 0
	s_xor_b32 s7, s5, 1
	s_or_b32 s6, s6, s7
	s_and_b32 s23, s23, s6
	s_cmp_gt_u32 s21, 2
	s_cselect_b32 s7, 1, 0
	s_and_b32 s7, s7, s5
	s_add_i32 s20, s20, s7
	v_readfirstlane_b32 s4, v5
	s_cmp_lg_u32 s4, 0
	s_cselect_b32 s5, 1, 0
	s_add_i32 s22, s22, s5
	s_cmp_eq_u32 s4, 32
	s_cselect_b32 s6, 1, 0
	s_xor_b32 s7, s5, 1
	s_or_b32 s6, s6, s7
	s_and_b32 s23, s23, s6
	s_cmp_gt_u32 s21, 3
	s_cselect_b32 s7, 1, 0
	s_and_b32 s7, s7, s5
	s_add_i32 s20, s20, s7
	v_readfirstlane_b32 s4, v6
	s_cmp_lg_u32 s4, 0
	s_cselect_b32 s5, 1, 0
	s_add_i32 s22, s22, s5
	s_cmp_eq_u32 s4, 32
	s_cselect_b32 s6, 1, 0
	s_xor_b32 s7, s5, 1
	s_or_b32 s6, s6, s7
	s_and_b32 s23, s23, s6
	s_cmp_gt_u32 s21, 4
	s_cselect_b32 s7, 1, 0
	s_and_b32 s7, s7, s5
	s_add_i32 s20, s20, s7
	v_readfirstlane_b32 s4, v7
	s_cmp_lg_u32 s4, 0
	s_cselect_b32 s5, 1, 0
	s_add_i32 s22, s22, s5
	s_cmp_eq_u32 s4, 32
	s_cselect_b32 s6, 1, 0
	s_xor_b32 s7, s5, 1
	s_or_b32 s6, s6, s7
	s_and_b32 s23, s23, s6
	s_cmp_gt_u32 s21, 5
	s_cselect_b32 s7, 1, 0
	s_and_b32 s7, s7, s5
	s_add_i32 s20, s20, s7
	v_readfirstlane_b32 s4, v8
	s_cmp_lg_u32 s4, 0
	s_cselect_b32 s5, 1, 0
	s_add_i32 s22, s22, s5
	s_cmp_eq_u32 s4, 32
	s_cselect_b32 s6, 1, 0
	s_xor_b32 s7, s5, 1
	s_or_b32 s6, s6, s7
	s_and_b32 s23, s23, s6
	s_cmp_gt_u32 s21, 6
	s_cselect_b32 s7, 1, 0
	s_and_b32 s7, s7, s5
	s_add_i32 s20, s20, s7
	v_readfirstlane_b32 s4, v9
	s_cmp_lg_u32 s4, 0
	s_cselect_b32 s5, 1, 0
	s_add_i32 s22, s22, s5
	s_cmp_eq_u32 s4, 32
	s_cselect_b32 s6, 1, 0
	s_xor_b32 s7, s5, 1
	s_or_b32 s6, s6, s7
	s_and_b32 s23, s23, s6
	s_cmp_gt_u32 s21, 7
	s_cselect_b32 s7, 1, 0
	s_and_b32 s7, s7, s5
	s_add_i32 s20, s20, s7
	v_readfirstlane_b32 s4, v10
	s_cmp_lg_u32 s4, 0
	s_cselect_b32 s5, 1, 0
	s_add_i32 s22, s22, s5
	s_cmp_eq_u32 s4, 32
	s_cselect_b32 s6, 1, 0
	s_xor_b32 s7, s5, 1
	s_or_b32 s6, s6, s7
	s_and_b32 s23, s23, s6
	s_cmp_gt_u32 s21, 8
	s_cselect_b32 s7, 1, 0
	s_and_b32 s7, s7, s5
	s_add_i32 s20, s20, s7
	v_readfirstlane_b32 s4, v11
	s_cmp_lg_u32 s4, 0
	s_cselect_b32 s5, 1, 0
	s_add_i32 s22, s22, s5
	s_cmp_eq_u32 s4, 32
	s_cselect_b32 s6, 1, 0
	s_xor_b32 s7, s5, 1
	s_or_b32 s6, s6, s7
	s_and_b32 s23, s23, s6
	s_cmp_gt_u32 s21, 9
	s_cselect_b32 s7, 1, 0
	s_and_b32 s7, s7, s5
	s_add_i32 s20, s20, s7
	v_readfirstlane_b32 s4, v12
	s_cmp_lg_u32 s4, 0
	s_cselect_b32 s5, 1, 0
	s_add_i32 s22, s22, s5
	s_cmp_eq_u32 s4, 32
	s_cselect_b32 s6, 1, 0
	s_xor_b32 s7, s5, 1
	s_or_b32 s6, s6, s7
	s_and_b32 s23, s23, s6
	s_cmp_gt_u32 s21, 10
	s_cselect_b32 s7, 1, 0
	s_and_b32 s7, s7, s5
	s_add_i32 s20, s20, s7
	v_readfirstlane_b32 s4, v13
	s_cmp_lg_u32 s4, 0
	s_cselect_b32 s5, 1, 0
	s_add_i32 s22, s22, s5
	s_cmp_eq_u32 s4, 32
	s_cselect_b32 s6, 1, 0
	s_xor_b32 s7, s5, 1
	s_or_b32 s6, s6, s7
	s_and_b32 s23, s23, s6
	s_cmp_gt_u32 s21, 11
	s_cselect_b32 s7, 1, 0
	s_and_b32 s7, s7, s5
	s_add_i32 s20, s20, s7
	v_readfirstlane_b32 s4, v14
	s_cmp_lg_u32 s4, 0
	s_cselect_b32 s5, 1, 0
	s_add_i32 s22, s22, s5
	s_cmp_eq_u32 s4, 32
	s_cselect_b32 s6, 1, 0
	s_xor_b32 s7, s5, 1
	s_or_b32 s6, s6, s7
	s_and_b32 s23, s23, s6
	s_cmp_gt_u32 s21, 12
	s_cselect_b32 s7, 1, 0
	s_and_b32 s7, s7, s5
	s_add_i32 s20, s20, s7
	v_readfirstlane_b32 s4, v15
	s_cmp_lg_u32 s4, 0
	s_cselect_b32 s5, 1, 0
	s_add_i32 s22, s22, s5
	s_cmp_eq_u32 s4, 32
	s_cselect_b32 s6, 1, 0
	s_xor_b32 s7, s5, 1
	s_or_b32 s6, s6, s7
	s_and_b32 s23, s23, s6
	s_cmp_gt_u32 s21, 13
	s_cselect_b32 s7, 1, 0
	s_and_b32 s7, s7, s5
	s_add_i32 s20, s20, s7
	v_readfirstlane_b32 s4, v16
	s_cmp_lg_u32 s4, 0
	s_cselect_b32 s5, 1, 0
	s_add_i32 s22, s22, s5
	s_cmp_eq_u32 s4, 32
	s_cselect_b32 s6, 1, 0
	s_xor_b32 s7, s5, 1
	s_or_b32 s6, s6, s7
	s_and_b32 s23, s23, s6
	s_cmp_gt_u32 s21, 14
	s_cselect_b32 s7, 1, 0
	s_and_b32 s7, s7, s5
	s_add_i32 s20, s20, s7
	v_readfirstlane_b32 s4, v17
	s_cmp_lg_u32 s4, 0
	s_cselect_b32 s5, 1, 0
	s_add_i32 s22, s22, s5
	s_cmp_eq_u32 s4, 32
	s_cselect_b32 s6, 1, 0
	s_xor_b32 s7, s5, 1
	s_or_b32 s6, s6, s7
	s_and_b32 s23, s23, s6
	s_cmp_gt_u32 s21, 15
	s_cselect_b32 s7, 1, 0
	s_and_b32 s7, s7, s5
	s_add_i32 s20, s20, s7
	v_readfirstlane_b32 s4, v19
	s_cmp_eq_u32 s22, 8
	s_cselect_b32 s6, 1, 0
	s_and_b32 s23, s23, s6
	s_cmpk_eq_i32 s3, 0x100
	s_cselect_b32 s6, 1, 0
	s_and_b32 s23, s23, s6
	s_cmp_lt_u32 s4, 32
	s_cselect_b32 s6, 1, 0
	s_and_b32 s23, s23, s6
	s_lshl_b32 s5, s20, 3
	s_and_b32 s6, s4, 7
	s_or_b32 s5, s5, s6
	s_lshr_b32 s6, s4, 3
	s_add_i32 s8, 0, 0x20168
	s_add_i32 s16, 0, 0x2016c
	s_add_i32 s17, 0, 0x20170
	v_mov_b32_e32 v0, s8
	v_mov_b32_e32 v3, s16
	v_mov_b32_e32 v4, s17
	v_mov_b32_e32 v5, s23
	v_mov_b32_e32 v1, s5
	v_mov_b32_e32 v2, s6
	ds_write_b32 v0, v5
	ds_write_b32 v3, v1
	ds_write_b32 v4, v2
